# FFN1/FFN2 k-loops: loop counter/pointer updates and next-iteration scalar selects moved into the tail of the last load segment (loader slack) instead of behind the loop-back barrier
# baseline (speedup 1.0000x reference)
.LBB0_1137:
	s_ashr_i32 s37, s36, 31
	s_lshl_b64 s[18:19], s[36:37], 19
	s_add_u32 s40, s96, s18
	s_addc_u32 s41, s97, s19
	s_and_b64 s[18:19], s[42:43], exec
	s_cselect_b32 s17, s41, s59
	s_cselect_b32 s37, s40, s58
	s_ashr_i32 s39, s38, 31
	s_lshl_b64 s[18:19], s[38:39], 19
	s_add_u32 s48, s5, s18
	s_addc_u32 s49, s6, s19
	s_and_b64 s[18:19], s[42:43], exec
	s_cselect_b32 s39, s49, s51
	s_cselect_b32 s46, s48, s50
	s_add_u32 s58, s58, 0x40080
	s_addc_u32 s59, s59, 0
	s_add_u32 s47, s50, 0x100
	s_addc_u32 s62, s51, 0
	s_mov_b32 s63, -2
	s_add_u32 s18, s58, 0xfffc0080
	s_addc_u32 s19, s59, -1
	s_add_i32 s20, 0, 0x10000
	s_cmp_eq_u32 s63, 12
	s_cselect_b32 s61, s17, s19
	s_cselect_b32 s60, s37, s18
	v_add_u32_e32 v140, s20, v143
	s_cselect_b32 s51, s39, s62
	s_cselect_b32 s50, s46, s47
	s_add_i32 s21, 0, 0x14000
	ds_read_b128 v[146:149], v140
	ds_read_b128 v[150:153], v140 offset:1024
	ds_read_b128 v[154:157], v140 offset:2048
	ds_read_b128 v[164:167], v140 offset:3072
	v_add_u32_e32 v140, s21, v143
	ds_read_b128 v[168:171], v140
	ds_read_b128 v[172:175], v140 offset:1024
	ds_read_b128 v[176:179], v140 offset:2048
	ds_read_b128 v[180:183], v140 offset:3072
	v_lshl_add_u64 v[140:141], s[58:59], 0, v[136:137]
	s_add_i32 m0, s8, 0xc000
	ds_read_b128 v[184:187], v144
	ds_read_b128 v[188:191], v144 offset:1024
	ds_read_b128 v[192:195], v144 offset:2048
	ds_read_b128 v[196:199], v144 offset:3072
	ds_read_b128 v[206:209], v144 offset:4096
	ds_read_b128 v[210:213], v144 offset:5120
	ds_read_b128 v[214:217], v144 offset:6144
	ds_read_b128 v[218:221], v144 offset:7168
	global_load_lds_dwordx4 v[140:141], off
	v_lshl_add_u64 v[140:141], s[58:59], 0, v[138:139]
	s_add_i32 m0, s8, 0xe000
	s_nop 0
	global_load_lds_dwordx4 v[140:141], off
	s_waitcnt vmcnt(8)
	s_waitcnt lgkmcnt(0)
	s_setprio 1
	s_barrier
	v_mfma_f32_16x16x32_bf16 v[124:127], v[146:149], v[184:187], 0
	v_mfma_f32_16x16x32_bf16 v[120:123], v[154:157], v[184:187], 0
	v_mfma_f32_16x16x32_bf16 v[108:111], v[146:149], v[192:195], 0
	v_mfma_f32_16x16x32_bf16 v[104:107], v[154:157], v[192:195], 0
	v_mfma_f32_16x16x32_bf16 v[92:95], v[146:149], v[206:209], 0
	v_mfma_f32_16x16x32_bf16 v[88:91], v[154:157], v[206:209], 0
	v_mfma_f32_16x16x32_bf16 v[76:79], v[146:149], v[214:217], 0
	v_mfma_f32_16x16x32_bf16 v[72:75], v[154:157], v[214:217], 0
	v_mfma_f32_16x16x32_bf16 v[124:127], v[150:153], v[188:191], v[124:127]
	v_mfma_f32_16x16x32_bf16 v[120:123], v[164:167], v[188:191], v[120:123]
	v_mfma_f32_16x16x32_bf16 v[108:111], v[150:153], v[196:199], v[108:111]
	v_mfma_f32_16x16x32_bf16 v[104:107], v[164:167], v[196:199], v[104:107]
	v_mfma_f32_16x16x32_bf16 v[92:95], v[150:153], v[210:213], v[92:95]
	v_mfma_f32_16x16x32_bf16 v[88:91], v[164:167], v[210:213], v[88:91]
	v_mfma_f32_16x16x32_bf16 v[76:79], v[150:153], v[218:221], v[76:79]
	v_mfma_f32_16x16x32_bf16 v[72:75], v[164:167], v[218:221], v[72:75]
	s_setprio 0
	s_setprio 1
	v_mfma_f32_16x16x32_bf16 v[116:119], v[168:171], v[184:187], 0
	v_mfma_f32_16x16x32_bf16 v[112:115], v[176:179], v[184:187], 0
	v_mfma_f32_16x16x32_bf16 v[100:103], v[168:171], v[192:195], 0
	v_mfma_f32_16x16x32_bf16 v[96:99], v[176:179], v[192:195], 0
	v_mfma_f32_16x16x32_bf16 v[84:87], v[168:171], v[206:209], 0
	v_mfma_f32_16x16x32_bf16 v[80:83], v[176:179], v[206:209], 0
	v_mfma_f32_16x16x32_bf16 v[68:71], v[168:171], v[214:217], 0
	v_mfma_f32_16x16x32_bf16 v[64:67], v[176:179], v[214:217], 0
	v_mfma_f32_16x16x32_bf16 v[116:119], v[172:175], v[188:191], v[116:119]
	v_mfma_f32_16x16x32_bf16 v[112:115], v[180:183], v[188:191], v[112:115]
	v_mfma_f32_16x16x32_bf16 v[100:103], v[172:175], v[196:199], v[100:103]
	v_mfma_f32_16x16x32_bf16 v[96:99], v[180:183], v[196:199], v[96:99]
	v_mfma_f32_16x16x32_bf16 v[84:87], v[172:175], v[210:213], v[84:87]
	v_mfma_f32_16x16x32_bf16 v[80:83], v[180:183], v[210:213], v[80:83]
	v_mfma_f32_16x16x32_bf16 v[68:71], v[172:175], v[218:221], v[68:71]
	v_mfma_f32_16x16x32_bf16 v[64:67], v[180:183], v[218:221], v[64:67]
	s_barrier
	s_setprio 0
	s_add_i32 s18, s20, s7
	v_lshl_add_u64 v[140:141], s[50:51], 0, v[132:133]
	s_mov_b32 m0, s18
	ds_read_b128 v[184:187], v144 offset:16384
	ds_read_b128 v[188:191], v144 offset:17408
	ds_read_b128 v[192:195], v144 offset:18432
	ds_read_b128 v[196:199], v144 offset:19456
	ds_read_b128 v[206:209], v144 offset:20480
	ds_read_b128 v[210:213], v144 offset:21504
	ds_read_b128 v[214:217], v144 offset:22528
	ds_read_b128 v[218:221], v144 offset:23552
	global_load_lds_dwordx4 v[140:141], off
	s_add_i32 m0, s18, 0x2000
	s_add_u32 s18, s50, 0x40000
	v_lshl_add_u64 v[158:159], s[50:51], 0, v[128:129]
	s_addc_u32 s19, s51, 0
	s_add_i32 s20, s21, s7
	global_load_lds_dwordx4 v[158:159], off
	v_lshl_add_u64 v[200:201], s[18:19], 0, v[132:133]
	s_mov_b32 m0, s20
	v_lshl_add_u64 v[222:223], s[60:61], 0, v[130:131]
	global_load_lds_dwordx4 v[200:201], off
	v_lshl_add_u64 v[200:201], s[18:19], 0, v[128:129]
	s_add_i32 m0, s20, 0x2000
	s_nop 0
	global_load_lds_dwordx4 v[200:201], off
	v_lshl_add_u64 v[200:201], s[60:61], 0, v[134:135]
	s_mov_b32 m0, s8
	s_nop 0
	global_load_lds_dwordx4 v[200:201], off
	s_mov_b32 m0, s9
	s_nop 0
	global_load_lds_dwordx4 v[222:223], off
	s_waitcnt vmcnt(8)
	s_waitcnt lgkmcnt(0)
	s_setprio 1
	s_barrier
	v_mfma_f32_16x16x32_bf16 v[60:63], v[146:149], v[184:187], 0
	v_mfma_f32_16x16x32_bf16 v[56:59], v[154:157], v[184:187], 0
	v_mfma_f32_16x16x32_bf16 v[44:47], v[146:149], v[192:195], 0
	v_mfma_f32_16x16x32_bf16 v[40:43], v[154:157], v[192:195], 0
	v_mfma_f32_16x16x32_bf16 v[28:31], v[146:149], v[206:209], 0
	v_mfma_f32_16x16x32_bf16 v[24:27], v[154:157], v[206:209], 0
	v_mfma_f32_16x16x32_bf16 v[12:15], v[146:149], v[214:217], 0
	v_mfma_f32_16x16x32_bf16 v[8:11], v[154:157], v[214:217], 0
	v_mfma_f32_16x16x32_bf16 v[60:63], v[150:153], v[188:191], v[60:63]
	v_mfma_f32_16x16x32_bf16 v[56:59], v[164:167], v[188:191], v[56:59]
	v_mfma_f32_16x16x32_bf16 v[44:47], v[150:153], v[196:199], v[44:47]
	v_mfma_f32_16x16x32_bf16 v[40:43], v[164:167], v[196:199], v[40:43]
	v_mfma_f32_16x16x32_bf16 v[28:31], v[150:153], v[210:213], v[28:31]
	v_mfma_f32_16x16x32_bf16 v[24:27], v[164:167], v[210:213], v[24:27]
	v_mfma_f32_16x16x32_bf16 v[12:15], v[150:153], v[218:221], v[12:15]
	v_mfma_f32_16x16x32_bf16 v[8:11], v[164:167], v[218:221], v[8:11]
	s_setprio 0
	s_setprio 1
	v_mfma_f32_16x16x32_bf16 v[52:55], v[168:171], v[184:187], 0
	v_mfma_f32_16x16x32_bf16 v[48:51], v[176:179], v[184:187], 0
	v_mfma_f32_16x16x32_bf16 v[36:39], v[168:171], v[192:195], 0
	v_mfma_f32_16x16x32_bf16 v[32:35], v[176:179], v[192:195], 0
	v_mfma_f32_16x16x32_bf16 v[20:23], v[168:171], v[206:209], 0
	v_mfma_f32_16x16x32_bf16 v[16:19], v[176:179], v[206:209], 0
	v_mfma_f32_16x16x32_bf16 v[4:7], v[168:171], v[214:217], 0
	v_mfma_f32_16x16x32_bf16 v[0:3], v[176:179], v[214:217], 0
	v_mfma_f32_16x16x32_bf16 v[52:55], v[172:175], v[188:191], v[52:55]
	v_mfma_f32_16x16x32_bf16 v[48:51], v[180:183], v[188:191], v[48:51]
	v_mfma_f32_16x16x32_bf16 v[36:39], v[172:175], v[196:199], v[36:39]
	v_mfma_f32_16x16x32_bf16 v[32:35], v[180:183], v[196:199], v[32:35]
	v_mfma_f32_16x16x32_bf16 v[20:23], v[172:175], v[210:213], v[20:23]
	v_mfma_f32_16x16x32_bf16 v[16:19], v[180:183], v[210:213], v[16:19]
	v_mfma_f32_16x16x32_bf16 v[4:7], v[172:175], v[218:221], v[4:7]
	v_mfma_f32_16x16x32_bf16 v[0:3], v[180:183], v[218:221], v[0:3]
	s_barrier
	s_setprio 0
	s_add_i32 s20, 0, 0x18000
	v_add_u32_e32 v145, s20, v143
	s_add_i32 s21, 0, 0x1c000
	ds_read_b128 v[146:149], v145
	ds_read_b128 v[150:153], v145 offset:1024
	ds_read_b128 v[154:157], v145 offset:2048
	ds_read_b128 v[164:167], v145 offset:3072
	v_add_u32_e32 v145, s21, v143
	ds_read_b128 v[168:171], v145
	ds_read_b128 v[172:175], v145 offset:1024
	ds_read_b128 v[176:179], v145 offset:2048
	ds_read_b128 v[180:183], v145 offset:3072
	s_add_u32 s18, s60, 0x40000
	s_addc_u32 s19, s61, 0
	s_mov_b32 m0, s10
	v_lshl_add_u64 v[224:225], s[18:19], 0, v[134:135]
	ds_read_b128 v[184:187], v144 offset:32768
	ds_read_b128 v[188:191], v144 offset:33792
	ds_read_b128 v[192:195], v144 offset:34816
	ds_read_b128 v[196:199], v144 offset:35840
	ds_read_b128 v[206:209], v144 offset:36864
	ds_read_b128 v[210:213], v144 offset:37888
	ds_read_b128 v[214:217], v144 offset:38912
	ds_read_b128 v[218:221], v144 offset:39936
	global_load_lds_dwordx4 v[224:225], off
	v_lshl_add_u64 v[224:225], s[18:19], 0, v[130:131]
	s_mov_b32 m0, s11
	s_nop 0
	global_load_lds_dwordx4 v[224:225], off
	s_waitcnt vmcnt(8)
	s_waitcnt lgkmcnt(0)
	s_setprio 1
	s_barrier
	v_mfma_f32_16x16x32_bf16 v[124:127], v[146:149], v[184:187], v[124:127]
	v_mfma_f32_16x16x32_bf16 v[120:123], v[154:157], v[184:187], v[120:123]
	v_mfma_f32_16x16x32_bf16 v[108:111], v[146:149], v[192:195], v[108:111]
	v_mfma_f32_16x16x32_bf16 v[104:107], v[154:157], v[192:195], v[104:107]
	v_mfma_f32_16x16x32_bf16 v[92:95], v[146:149], v[206:209], v[92:95]
	v_mfma_f32_16x16x32_bf16 v[88:91], v[154:157], v[206:209], v[88:91]
	v_mfma_f32_16x16x32_bf16 v[76:79], v[146:149], v[214:217], v[76:79]
	v_mfma_f32_16x16x32_bf16 v[72:75], v[154:157], v[214:217], v[72:75]
	v_mfma_f32_16x16x32_bf16 v[124:127], v[150:153], v[188:191], v[124:127]
	v_mfma_f32_16x16x32_bf16 v[120:123], v[164:167], v[188:191], v[120:123]
	v_mfma_f32_16x16x32_bf16 v[108:111], v[150:153], v[196:199], v[108:111]
	v_mfma_f32_16x16x32_bf16 v[104:107], v[164:167], v[196:199], v[104:107]
	v_mfma_f32_16x16x32_bf16 v[92:95], v[150:153], v[210:213], v[92:95]
	v_mfma_f32_16x16x32_bf16 v[88:91], v[164:167], v[210:213], v[88:91]
	v_mfma_f32_16x16x32_bf16 v[76:79], v[150:153], v[218:221], v[76:79]
	v_mfma_f32_16x16x32_bf16 v[72:75], v[164:167], v[218:221], v[72:75]
	s_setprio 0
	s_setprio 1
	v_mfma_f32_16x16x32_bf16 v[116:119], v[168:171], v[184:187], v[116:119]
	v_mfma_f32_16x16x32_bf16 v[112:115], v[176:179], v[184:187], v[112:115]
	v_mfma_f32_16x16x32_bf16 v[100:103], v[168:171], v[192:195], v[100:103]
	v_mfma_f32_16x16x32_bf16 v[96:99], v[176:179], v[192:195], v[96:99]
	v_mfma_f32_16x16x32_bf16 v[84:87], v[168:171], v[206:209], v[84:87]
	v_mfma_f32_16x16x32_bf16 v[80:83], v[176:179], v[206:209], v[80:83]
	v_mfma_f32_16x16x32_bf16 v[68:71], v[168:171], v[214:217], v[68:71]
	v_mfma_f32_16x16x32_bf16 v[64:67], v[176:179], v[214:217], v[64:67]
	v_mfma_f32_16x16x32_bf16 v[116:119], v[172:175], v[188:191], v[116:119]
	v_mfma_f32_16x16x32_bf16 v[112:115], v[180:183], v[188:191], v[112:115]
	v_mfma_f32_16x16x32_bf16 v[100:103], v[172:175], v[196:199], v[100:103]
	v_mfma_f32_16x16x32_bf16 v[96:99], v[180:183], v[196:199], v[96:99]
	v_mfma_f32_16x16x32_bf16 v[84:87], v[172:175], v[210:213], v[84:87]
	v_mfma_f32_16x16x32_bf16 v[80:83], v[180:183], v[210:213], v[80:83]
	v_mfma_f32_16x16x32_bf16 v[68:71], v[172:175], v[218:221], v[68:71]
	v_mfma_f32_16x16x32_bf16 v[64:67], v[180:183], v[218:221], v[64:67]
	s_barrier
	s_setprio 0
	s_add_i32 s18, s20, s7
	v_lshl_add_u64 v[140:141], v[140:141], 0, s[76:77]
	s_mov_b32 m0, s18
	ds_read_b128 v[184:187], v144 offset:49152
	ds_read_b128 v[188:191], v144 offset:50176
	ds_read_b128 v[192:195], v144 offset:51200
	ds_read_b128 v[196:199], v144 offset:52224
	ds_read_b128 v[206:209], v144 offset:53248
	ds_read_b128 v[210:213], v144 offset:54272
	ds_read_b128 v[214:217], v144 offset:55296
	ds_read_b128 v[218:221], v144 offset:56320
	global_load_lds_dwordx4 v[140:141], off
	s_add_i32 m0, s18, 0x2000
	s_add_u32 s18, s50, 0x40080
	v_lshl_add_u64 v[140:141], v[158:159], 0, s[76:77]
	s_addc_u32 s19, s51, 0
	s_add_i32 s20, s21, s7
	global_load_lds_dwordx4 v[140:141], off
	v_lshl_add_u64 v[140:141], s[18:19], 0, v[132:133]
	s_mov_b32 m0, s20
	s_nop 0
	global_load_lds_dwordx4 v[140:141], off
	v_lshl_add_u64 v[140:141], s[18:19], 0, v[128:129]
	s_add_i32 m0, s20, 0x2000
	s_nop 0
	global_load_lds_dwordx4 v[140:141], off
	v_lshl_add_u64 v[140:141], v[200:201], 0, s[76:77]
	s_mov_b32 m0, s12
	s_nop 0
	global_load_lds_dwordx4 v[140:141], off
	v_lshl_add_u64 v[140:141], v[222:223], 0, s[76:77]
	s_mov_b32 m0, s13
	s_nop 0
	global_load_lds_dwordx4 v[140:141], off
	s_add_i32 s63, s63, 2
	s_add_u32 s58, s58, 0x100
	s_addc_u32 s59, s59, 0
	s_add_u32 s47, s47, 0x100
	s_addc_u32 s62, s62, 0
	s_cmp_gt_u32 s63, 13
	s_cbranch_scc1 .Lrs_1138_a
	s_add_u32 s18, s58, 0xfffc0080
	s_addc_u32 s19, s59, -1
	s_add_i32 s20, 0, 0x10000
	s_cmp_eq_u32 s63, 12
	s_cselect_b32 s61, s17, s19
	s_cselect_b32 s60, s37, s18
	s_cselect_b32 s51, s39, s62
	s_cselect_b32 s50, s46, s47
	s_add_i32 s21, 0, 0x14000
.Lrs_1138_a:
	s_waitcnt vmcnt(8)
	s_waitcnt lgkmcnt(0)
	s_setprio 1
	s_barrier
	v_mfma_f32_16x16x32_bf16 v[60:63], v[146:149], v[184:187], v[60:63]
	v_mfma_f32_16x16x32_bf16 v[56:59], v[154:157], v[184:187], v[56:59]
	v_mfma_f32_16x16x32_bf16 v[44:47], v[146:149], v[192:195], v[44:47]
	v_mfma_f32_16x16x32_bf16 v[40:43], v[154:157], v[192:195], v[40:43]
	v_mfma_f32_16x16x32_bf16 v[28:31], v[146:149], v[206:209], v[28:31]
	v_mfma_f32_16x16x32_bf16 v[24:27], v[154:157], v[206:209], v[24:27]
	v_mfma_f32_16x16x32_bf16 v[12:15], v[146:149], v[214:217], v[12:15]
	v_mfma_f32_16x16x32_bf16 v[8:11], v[154:157], v[214:217], v[8:11]
	v_mfma_f32_16x16x32_bf16 v[60:63], v[150:153], v[188:191], v[60:63]
	v_mfma_f32_16x16x32_bf16 v[56:59], v[164:167], v[188:191], v[56:59]
	v_mfma_f32_16x16x32_bf16 v[44:47], v[150:153], v[196:199], v[44:47]
	v_mfma_f32_16x16x32_bf16 v[40:43], v[164:167], v[196:199], v[40:43]
	v_mfma_f32_16x16x32_bf16 v[28:31], v[150:153], v[210:213], v[28:31]
	v_mfma_f32_16x16x32_bf16 v[24:27], v[164:167], v[210:213], v[24:27]
	v_mfma_f32_16x16x32_bf16 v[12:15], v[150:153], v[218:221], v[12:15]
	v_mfma_f32_16x16x32_bf16 v[8:11], v[164:167], v[218:221], v[8:11]
	s_setprio 0
	s_setprio 1
	v_mfma_f32_16x16x32_bf16 v[52:55], v[168:171], v[184:187], v[52:55]
	v_mfma_f32_16x16x32_bf16 v[48:51], v[176:179], v[184:187], v[48:51]
	v_mfma_f32_16x16x32_bf16 v[36:39], v[168:171], v[192:195], v[36:39]
	v_mfma_f32_16x16x32_bf16 v[32:35], v[176:179], v[192:195], v[32:35]
	v_mfma_f32_16x16x32_bf16 v[20:23], v[168:171], v[206:209], v[20:23]
	v_mfma_f32_16x16x32_bf16 v[16:19], v[176:179], v[206:209], v[16:19]
	v_mfma_f32_16x16x32_bf16 v[4:7], v[168:171], v[214:217], v[4:7]
	v_mfma_f32_16x16x32_bf16 v[0:3], v[176:179], v[214:217], v[0:3]
	v_mfma_f32_16x16x32_bf16 v[52:55], v[172:175], v[188:191], v[52:55]
	v_mfma_f32_16x16x32_bf16 v[48:51], v[180:183], v[188:191], v[48:51]
	v_mfma_f32_16x16x32_bf16 v[36:39], v[172:175], v[196:199], v[36:39]
	v_mfma_f32_16x16x32_bf16 v[32:35], v[180:183], v[196:199], v[32:35]
	v_mfma_f32_16x16x32_bf16 v[20:23], v[172:175], v[210:213], v[20:23]
	v_mfma_f32_16x16x32_bf16 v[16:19], v[180:183], v[210:213], v[16:19]
	v_mfma_f32_16x16x32_bf16 v[4:7], v[172:175], v[218:221], v[4:7]
	v_mfma_f32_16x16x32_bf16 v[0:3], v[180:183], v[218:221], v[0:3]
	s_barrier
	s_setprio 0
	s_cmp_gt_u32 s63, 13
	s_cbranch_scc0 .Lrot_1138
	s_branch .Lpeel_x_1138
.LBB0_1138:
.Lrot_1138:
	v_add_u32_e32 v140, s20, v143
	ds_read_b128 v[146:149], v140
	ds_read_b128 v[150:153], v140 offset:1024
	ds_read_b128 v[154:157], v140 offset:2048
	ds_read_b128 v[164:167], v140 offset:3072
	v_add_u32_e32 v140, s21, v143
	ds_read_b128 v[168:171], v140
	ds_read_b128 v[172:175], v140 offset:1024
	ds_read_b128 v[176:179], v140 offset:2048
	ds_read_b128 v[180:183], v140 offset:3072
	v_lshl_add_u64 v[140:141], s[58:59], 0, v[136:137]
	s_add_i32 m0, s8, 0xc000
	ds_read_b128 v[184:187], v144
	ds_read_b128 v[188:191], v144 offset:1024
	ds_read_b128 v[192:195], v144 offset:2048
	ds_read_b128 v[196:199], v144 offset:3072
	ds_read_b128 v[206:209], v144 offset:4096
	ds_read_b128 v[210:213], v144 offset:5120
	ds_read_b128 v[214:217], v144 offset:6144
	ds_read_b128 v[218:221], v144 offset:7168
	global_load_lds_dwordx4 v[140:141], off
	v_lshl_add_u64 v[140:141], s[58:59], 0, v[138:139]
	s_add_i32 m0, s8, 0xe000
	s_nop 0
	global_load_lds_dwordx4 v[140:141], off
	s_waitcnt vmcnt(8)
	s_waitcnt lgkmcnt(0)
	s_setprio 1
	s_barrier
	v_mfma_f32_16x16x32_bf16 v[124:127], v[146:149], v[184:187], v[124:127]
	v_mfma_f32_16x16x32_bf16 v[120:123], v[154:157], v[184:187], v[120:123]
	v_mfma_f32_16x16x32_bf16 v[108:111], v[146:149], v[192:195], v[108:111]
	v_mfma_f32_16x16x32_bf16 v[104:107], v[154:157], v[192:195], v[104:107]
	v_mfma_f32_16x16x32_bf16 v[92:95], v[146:149], v[206:209], v[92:95]
	v_mfma_f32_16x16x32_bf16 v[88:91], v[154:157], v[206:209], v[88:91]
	v_mfma_f32_16x16x32_bf16 v[76:79], v[146:149], v[214:217], v[76:79]
	v_mfma_f32_16x16x32_bf16 v[72:75], v[154:157], v[214:217], v[72:75]
	v_mfma_f32_16x16x32_bf16 v[124:127], v[150:153], v[188:191], v[124:127]
	v_mfma_f32_16x16x32_bf16 v[120:123], v[164:167], v[188:191], v[120:123]
	v_mfma_f32_16x16x32_bf16 v[108:111], v[150:153], v[196:199], v[108:111]
	v_mfma_f32_16x16x32_bf16 v[104:107], v[164:167], v[196:199], v[104:107]
	v_mfma_f32_16x16x32_bf16 v[92:95], v[150:153], v[210:213], v[92:95]
	v_mfma_f32_16x16x32_bf16 v[88:91], v[164:167], v[210:213], v[88:91]
	v_mfma_f32_16x16x32_bf16 v[76:79], v[150:153], v[218:221], v[76:79]
	v_mfma_f32_16x16x32_bf16 v[72:75], v[164:167], v[218:221], v[72:75]
	s_setprio 0
	s_setprio 1
	v_mfma_f32_16x16x32_bf16 v[116:119], v[168:171], v[184:187], v[116:119]
	v_mfma_f32_16x16x32_bf16 v[112:115], v[176:179], v[184:187], v[112:115]
	v_mfma_f32_16x16x32_bf16 v[100:103], v[168:171], v[192:195], v[100:103]
	v_mfma_f32_16x16x32_bf16 v[96:99], v[176:179], v[192:195], v[96:99]
	v_mfma_f32_16x16x32_bf16 v[84:87], v[168:171], v[206:209], v[84:87]
	v_mfma_f32_16x16x32_bf16 v[80:83], v[176:179], v[206:209], v[80:83]
	v_mfma_f32_16x16x32_bf16 v[68:71], v[168:171], v[214:217], v[68:71]
	v_mfma_f32_16x16x32_bf16 v[64:67], v[176:179], v[214:217], v[64:67]
	v_mfma_f32_16x16x32_bf16 v[116:119], v[172:175], v[188:191], v[116:119]
	v_mfma_f32_16x16x32_bf16 v[112:115], v[180:183], v[188:191], v[112:115]
	v_mfma_f32_16x16x32_bf16 v[100:103], v[172:175], v[196:199], v[100:103]
	v_mfma_f32_16x16x32_bf16 v[96:99], v[180:183], v[196:199], v[96:99]
	v_mfma_f32_16x16x32_bf16 v[84:87], v[172:175], v[210:213], v[84:87]
	v_mfma_f32_16x16x32_bf16 v[80:83], v[180:183], v[210:213], v[80:83]
	v_mfma_f32_16x16x32_bf16 v[68:71], v[172:175], v[218:221], v[68:71]
	v_mfma_f32_16x16x32_bf16 v[64:67], v[180:183], v[218:221], v[64:67]
	s_barrier
	s_setprio 0
	s_add_i32 s18, s20, s7
	v_lshl_add_u64 v[140:141], s[50:51], 0, v[132:133]
	s_mov_b32 m0, s18
	ds_read_b128 v[184:187], v144 offset:16384
	ds_read_b128 v[188:191], v144 offset:17408
	ds_read_b128 v[192:195], v144 offset:18432
	ds_read_b128 v[196:199], v144 offset:19456
	ds_read_b128 v[206:209], v144 offset:20480
	ds_read_b128 v[210:213], v144 offset:21504
	ds_read_b128 v[214:217], v144 offset:22528
	ds_read_b128 v[218:221], v144 offset:23552
	global_load_lds_dwordx4 v[140:141], off
	s_add_i32 m0, s18, 0x2000
	s_add_u32 s18, s50, 0x40000
	v_lshl_add_u64 v[158:159], s[50:51], 0, v[128:129]
	s_addc_u32 s19, s51, 0
	s_add_i32 s20, s21, s7
	global_load_lds_dwordx4 v[158:159], off
	v_lshl_add_u64 v[200:201], s[18:19], 0, v[132:133]
	s_mov_b32 m0, s20
	v_lshl_add_u64 v[222:223], s[60:61], 0, v[130:131]
	global_load_lds_dwordx4 v[200:201], off
	v_lshl_add_u64 v[200:201], s[18:19], 0, v[128:129]
	s_add_i32 m0, s20, 0x2000
	s_nop 0
	global_load_lds_dwordx4 v[200:201], off
	v_lshl_add_u64 v[200:201], s[60:61], 0, v[134:135]
	s_mov_b32 m0, s8
	s_nop 0
	global_load_lds_dwordx4 v[200:201], off
	s_mov_b32 m0, s9
	s_nop 0
	global_load_lds_dwordx4 v[222:223], off
	s_waitcnt vmcnt(8)
	s_waitcnt lgkmcnt(0)
	s_setprio 1
	s_barrier
	v_mfma_f32_16x16x32_bf16 v[60:63], v[146:149], v[184:187], v[60:63]
	v_mfma_f32_16x16x32_bf16 v[56:59], v[154:157], v[184:187], v[56:59]
	v_mfma_f32_16x16x32_bf16 v[44:47], v[146:149], v[192:195], v[44:47]
	v_mfma_f32_16x16x32_bf16 v[40:43], v[154:157], v[192:195], v[40:43]
	v_mfma_f32_16x16x32_bf16 v[28:31], v[146:149], v[206:209], v[28:31]
	v_mfma_f32_16x16x32_bf16 v[24:27], v[154:157], v[206:209], v[24:27]
	v_mfma_f32_16x16x32_bf16 v[12:15], v[146:149], v[214:217], v[12:15]
	v_mfma_f32_16x16x32_bf16 v[8:11], v[154:157], v[214:217], v[8:11]
	v_mfma_f32_16x16x32_bf16 v[60:63], v[150:153], v[188:191], v[60:63]
	v_mfma_f32_16x16x32_bf16 v[56:59], v[164:167], v[188:191], v[56:59]
	v_mfma_f32_16x16x32_bf16 v[44:47], v[150:153], v[196:199], v[44:47]
	v_mfma_f32_16x16x32_bf16 v[40:43], v[164:167], v[196:199], v[40:43]
	v_mfma_f32_16x16x32_bf16 v[28:31], v[150:153], v[210:213], v[28:31]
	v_mfma_f32_16x16x32_bf16 v[24:27], v[164:167], v[210:213], v[24:27]
	v_mfma_f32_16x16x32_bf16 v[12:15], v[150:153], v[218:221], v[12:15]
	v_mfma_f32_16x16x32_bf16 v[8:11], v[164:167], v[218:221], v[8:11]
	s_setprio 0
	s_setprio 1
	v_mfma_f32_16x16x32_bf16 v[52:55], v[168:171], v[184:187], v[52:55]
	v_mfma_f32_16x16x32_bf16 v[48:51], v[176:179], v[184:187], v[48:51]
	v_mfma_f32_16x16x32_bf16 v[36:39], v[168:171], v[192:195], v[36:39]
	v_mfma_f32_16x16x32_bf16 v[32:35], v[176:179], v[192:195], v[32:35]
	v_mfma_f32_16x16x32_bf16 v[20:23], v[168:171], v[206:209], v[20:23]
	v_mfma_f32_16x16x32_bf16 v[16:19], v[176:179], v[206:209], v[16:19]
	v_mfma_f32_16x16x32_bf16 v[4:7], v[168:171], v[214:217], v[4:7]
	v_mfma_f32_16x16x32_bf16 v[0:3], v[176:179], v[214:217], v[0:3]
	v_mfma_f32_16x16x32_bf16 v[52:55], v[172:175], v[188:191], v[52:55]
	v_mfma_f32_16x16x32_bf16 v[48:51], v[180:183], v[188:191], v[48:51]
	v_mfma_f32_16x16x32_bf16 v[36:39], v[172:175], v[196:199], v[36:39]
	v_mfma_f32_16x16x32_bf16 v[32:35], v[180:183], v[196:199], v[32:35]
	v_mfma_f32_16x16x32_bf16 v[20:23], v[172:175], v[210:213], v[20:23]
	v_mfma_f32_16x16x32_bf16 v[16:19], v[180:183], v[210:213], v[16:19]
	v_mfma_f32_16x16x32_bf16 v[4:7], v[172:175], v[218:221], v[4:7]
	v_mfma_f32_16x16x32_bf16 v[0:3], v[180:183], v[218:221], v[0:3]
	s_barrier
	s_setprio 0
	s_add_i32 s20, 0, 0x18000
	v_add_u32_e32 v145, s20, v143
	s_add_i32 s21, 0, 0x1c000
	ds_read_b128 v[146:149], v145
	ds_read_b128 v[150:153], v145 offset:1024
	ds_read_b128 v[154:157], v145 offset:2048
	ds_read_b128 v[164:167], v145 offset:3072
	v_add_u32_e32 v145, s21, v143
	ds_read_b128 v[168:171], v145
	ds_read_b128 v[172:175], v145 offset:1024
	ds_read_b128 v[176:179], v145 offset:2048
	ds_read_b128 v[180:183], v145 offset:3072
	s_add_u32 s18, s60, 0x40000
	s_addc_u32 s19, s61, 0
	s_mov_b32 m0, s10
	v_lshl_add_u64 v[224:225], s[18:19], 0, v[134:135]
	ds_read_b128 v[184:187], v144 offset:32768
	ds_read_b128 v[188:191], v144 offset:33792
	ds_read_b128 v[192:195], v144 offset:34816
	ds_read_b128 v[196:199], v144 offset:35840
	ds_read_b128 v[206:209], v144 offset:36864
	ds_read_b128 v[210:213], v144 offset:37888
	ds_read_b128 v[214:217], v144 offset:38912
	ds_read_b128 v[218:221], v144 offset:39936
	global_load_lds_dwordx4 v[224:225], off
	v_lshl_add_u64 v[224:225], s[18:19], 0, v[130:131]
	s_mov_b32 m0, s11
	s_nop 0
	global_load_lds_dwordx4 v[224:225], off
	s_waitcnt vmcnt(8)
	s_waitcnt lgkmcnt(0)
	s_setprio 1
	s_barrier
	v_mfma_f32_16x16x32_bf16 v[124:127], v[146:149], v[184:187], v[124:127]
	v_mfma_f32_16x16x32_bf16 v[120:123], v[154:157], v[184:187], v[120:123]
	v_mfma_f32_16x16x32_bf16 v[108:111], v[146:149], v[192:195], v[108:111]
	v_mfma_f32_16x16x32_bf16 v[104:107], v[154:157], v[192:195], v[104:107]
	v_mfma_f32_16x16x32_bf16 v[92:95], v[146:149], v[206:209], v[92:95]
	v_mfma_f32_16x16x32_bf16 v[88:91], v[154:157], v[206:209], v[88:91]
	v_mfma_f32_16x16x32_bf16 v[76:79], v[146:149], v[214:217], v[76:79]
	v_mfma_f32_16x16x32_bf16 v[72:75], v[154:157], v[214:217], v[72:75]
	v_mfma_f32_16x16x32_bf16 v[124:127], v[150:153], v[188:191], v[124:127]
	v_mfma_f32_16x16x32_bf16 v[120:123], v[164:167], v[188:191], v[120:123]
	v_mfma_f32_16x16x32_bf16 v[108:111], v[150:153], v[196:199], v[108:111]
	v_mfma_f32_16x16x32_bf16 v[104:107], v[164:167], v[196:199], v[104:107]
	v_mfma_f32_16x16x32_bf16 v[92:95], v[150:153], v[210:213], v[92:95]
	v_mfma_f32_16x16x32_bf16 v[88:91], v[164:167], v[210:213], v[88:91]
	v_mfma_f32_16x16x32_bf16 v[76:79], v[150:153], v[218:221], v[76:79]
	v_mfma_f32_16x16x32_bf16 v[72:75], v[164:167], v[218:221], v[72:75]
	s_setprio 0
	s_setprio 1
	v_mfma_f32_16x16x32_bf16 v[116:119], v[168:171], v[184:187], v[116:119]
	v_mfma_f32_16x16x32_bf16 v[112:115], v[176:179], v[184:187], v[112:115]
	v_mfma_f32_16x16x32_bf16 v[100:103], v[168:171], v[192:195], v[100:103]
	v_mfma_f32_16x16x32_bf16 v[96:99], v[176:179], v[192:195], v[96:99]
	v_mfma_f32_16x16x32_bf16 v[84:87], v[168:171], v[206:209], v[84:87]
	v_mfma_f32_16x16x32_bf16 v[80:83], v[176:179], v[206:209], v[80:83]
	v_mfma_f32_16x16x32_bf16 v[68:71], v[168:171], v[214:217], v[68:71]
	v_mfma_f32_16x16x32_bf16 v[64:67], v[176:179], v[214:217], v[64:67]
	v_mfma_f32_16x16x32_bf16 v[116:119], v[172:175], v[188:191], v[116:119]
	v_mfma_f32_16x16x32_bf16 v[112:115], v[180:183], v[188:191], v[112:115]
	v_mfma_f32_16x16x32_bf16 v[100:103], v[172:175], v[196:199], v[100:103]
	v_mfma_f32_16x16x32_bf16 v[96:99], v[180:183], v[196:199], v[96:99]
	v_mfma_f32_16x16x32_bf16 v[84:87], v[172:175], v[210:213], v[84:87]
	v_mfma_f32_16x16x32_bf16 v[80:83], v[180:183], v[210:213], v[80:83]
	v_mfma_f32_16x16x32_bf16 v[68:71], v[172:175], v[218:221], v[68:71]
	v_mfma_f32_16x16x32_bf16 v[64:67], v[180:183], v[218:221], v[64:67]
	s_barrier
	s_setprio 0
	s_add_i32 s18, s20, s7
	v_lshl_add_u64 v[140:141], v[140:141], 0, s[76:77]
	s_mov_b32 m0, s18
	ds_read_b128 v[184:187], v144 offset:49152
	ds_read_b128 v[188:191], v144 offset:50176
	ds_read_b128 v[192:195], v144 offset:51200
	ds_read_b128 v[196:199], v144 offset:52224
	ds_read_b128 v[206:209], v144 offset:53248
	ds_read_b128 v[210:213], v144 offset:54272
	ds_read_b128 v[214:217], v144 offset:55296
	ds_read_b128 v[218:221], v144 offset:56320
	global_load_lds_dwordx4 v[140:141], off
	s_add_i32 m0, s18, 0x2000
	s_add_u32 s18, s50, 0x40080
	v_lshl_add_u64 v[140:141], v[158:159], 0, s[76:77]
	s_addc_u32 s19, s51, 0
	s_add_i32 s20, s21, s7
	global_load_lds_dwordx4 v[140:141], off
	v_lshl_add_u64 v[140:141], s[18:19], 0, v[132:133]
	s_mov_b32 m0, s20
	s_nop 0
	global_load_lds_dwordx4 v[140:141], off
	v_lshl_add_u64 v[140:141], s[18:19], 0, v[128:129]
	s_add_i32 m0, s20, 0x2000
	s_nop 0
	global_load_lds_dwordx4 v[140:141], off
	v_lshl_add_u64 v[140:141], v[200:201], 0, s[76:77]
	s_mov_b32 m0, s12
	s_nop 0
	global_load_lds_dwordx4 v[140:141], off
	v_lshl_add_u64 v[140:141], v[222:223], 0, s[76:77]
	s_mov_b32 m0, s13
	s_nop 0
	global_load_lds_dwordx4 v[140:141], off
	s_add_i32 s63, s63, 2
	s_add_u32 s58, s58, 0x100
	s_addc_u32 s59, s59, 0
	s_add_u32 s47, s47, 0x100
	s_addc_u32 s62, s62, 0
	s_cmp_gt_u32 s63, 13
	s_cbranch_scc1 .Lrs_1138_b
	s_add_u32 s18, s58, 0xfffc0080
	s_addc_u32 s19, s59, -1
	s_add_i32 s20, 0, 0x10000
	s_cmp_eq_u32 s63, 12
	s_cselect_b32 s61, s17, s19
	s_cselect_b32 s60, s37, s18
	s_cselect_b32 s51, s39, s62
	s_cselect_b32 s50, s46, s47
	s_add_i32 s21, 0, 0x14000
.Lrs_1138_b:
	s_waitcnt vmcnt(8)
	s_waitcnt lgkmcnt(0)
	s_setprio 1
	s_barrier
	v_mfma_f32_16x16x32_bf16 v[60:63], v[146:149], v[184:187], v[60:63]
	v_mfma_f32_16x16x32_bf16 v[56:59], v[154:157], v[184:187], v[56:59]
	v_mfma_f32_16x16x32_bf16 v[44:47], v[146:149], v[192:195], v[44:47]
	v_mfma_f32_16x16x32_bf16 v[40:43], v[154:157], v[192:195], v[40:43]
	v_mfma_f32_16x16x32_bf16 v[28:31], v[146:149], v[206:209], v[28:31]
	v_mfma_f32_16x16x32_bf16 v[24:27], v[154:157], v[206:209], v[24:27]
	v_mfma_f32_16x16x32_bf16 v[12:15], v[146:149], v[214:217], v[12:15]
	v_mfma_f32_16x16x32_bf16 v[8:11], v[154:157], v[214:217], v[8:11]
	v_mfma_f32_16x16x32_bf16 v[60:63], v[150:153], v[188:191], v[60:63]
	v_mfma_f32_16x16x32_bf16 v[56:59], v[164:167], v[188:191], v[56:59]
	v_mfma_f32_16x16x32_bf16 v[44:47], v[150:153], v[196:199], v[44:47]
	v_mfma_f32_16x16x32_bf16 v[40:43], v[164:167], v[196:199], v[40:43]
	v_mfma_f32_16x16x32_bf16 v[28:31], v[150:153], v[210:213], v[28:31]
	v_mfma_f32_16x16x32_bf16 v[24:27], v[164:167], v[210:213], v[24:27]
	v_mfma_f32_16x16x32_bf16 v[12:15], v[150:153], v[218:221], v[12:15]
	v_mfma_f32_16x16x32_bf16 v[8:11], v[164:167], v[218:221], v[8:11]
	s_setprio 0
	s_setprio 1
	v_mfma_f32_16x16x32_bf16 v[52:55], v[168:171], v[184:187], v[52:55]
	v_mfma_f32_16x16x32_bf16 v[48:51], v[176:179], v[184:187], v[48:51]
	v_mfma_f32_16x16x32_bf16 v[36:39], v[168:171], v[192:195], v[36:39]
	v_mfma_f32_16x16x32_bf16 v[32:35], v[176:179], v[192:195], v[32:35]
	v_mfma_f32_16x16x32_bf16 v[20:23], v[168:171], v[206:209], v[20:23]
	v_mfma_f32_16x16x32_bf16 v[16:19], v[176:179], v[206:209], v[16:19]
	v_mfma_f32_16x16x32_bf16 v[4:7], v[168:171], v[214:217], v[4:7]
	v_mfma_f32_16x16x32_bf16 v[0:3], v[176:179], v[214:217], v[0:3]
	v_mfma_f32_16x16x32_bf16 v[52:55], v[172:175], v[188:191], v[52:55]
	v_mfma_f32_16x16x32_bf16 v[48:51], v[180:183], v[188:191], v[48:51]
	v_mfma_f32_16x16x32_bf16 v[36:39], v[172:175], v[196:199], v[36:39]
	v_mfma_f32_16x16x32_bf16 v[32:35], v[180:183], v[196:199], v[32:35]
	v_mfma_f32_16x16x32_bf16 v[20:23], v[172:175], v[210:213], v[20:23]
	v_mfma_f32_16x16x32_bf16 v[16:19], v[180:183], v[210:213], v[16:19]
	v_mfma_f32_16x16x32_bf16 v[4:7], v[172:175], v[218:221], v[4:7]
	v_mfma_f32_16x16x32_bf16 v[0:3], v[180:183], v[218:221], v[0:3]
	s_barrier
	s_setprio 0
	s_cmp_gt_u32 s63, 13
	s_cbranch_scc0 .Lrot_1138

.LBB0_1209:
	s_add_u32 s54, s48, 0x100
	s_addc_u32 s60, s49, 0
	s_mov_b32 s61, -2
	s_add_u32 s48, s42, 0x100
	s_addc_u32 s49, s43, 0
	s_add_i32 s18, 0, 0x10000
	s_cmp_eq_u32 s61, 40
	s_cselect_b32 s59, s39, s49
	s_cselect_b32 s58, s38, s48
	s_cselect_b32 s51, s41, s60
	s_cselect_b32 s50, s40, s54
	s_add_i32 s20, 0, 0x14000
	v_add_u32_e32 v140, s18, v174
	v_add_u32_e32 v162, s20, v174
	ds_read_b128 v[128:131], v140
	ds_read_b128 v[132:135], v140 offset:1024
	ds_read_b128 v[136:139], v140 offset:2048
	ds_read_b128 v[140:143], v140 offset:3072
	ds_read_b128 v[156:159], v162
	ds_read_b128 v[164:167], v162 offset:1024
	ds_read_b128 v[168:171], v162 offset:2048
	ds_read_b128 v[176:179], v162 offset:3072
	v_lshl_add_u64 v[200:201], s[42:43], 0, v[152:153]
	s_add_i32 m0, s4, 0xc000
	ds_read_b128 v[180:183], v175
	ds_read_b128 v[184:187], v175 offset:1024
	ds_read_b128 v[188:191], v175 offset:2048
	ds_read_b128 v[192:195], v175 offset:3072
	ds_read_b128 v[196:199], v175 offset:4096
	ds_read_b128 v[206:209], v175 offset:5120
	ds_read_b128 v[210:213], v175 offset:6144
	ds_read_b128 v[214:217], v175 offset:7168
	global_load_lds_dwordx4 v[200:201], off
	v_lshl_add_u64 v[200:201], s[42:43], 0, v[154:155]
	s_add_i32 m0, s4, 0xe000
	s_nop 0
	global_load_lds_dwordx4 v[200:201], off
	s_waitcnt vmcnt(8)
	s_waitcnt lgkmcnt(0)
	s_setprio 1
	s_barrier
	v_mfma_f32_16x16x32_bf16 v[124:127], v[128:131], v[180:183], 0
	v_mfma_f32_16x16x32_bf16 v[120:123], v[136:139], v[180:183], 0
	v_mfma_f32_16x16x32_bf16 v[112:115], v[128:131], v[188:191], 0
	v_mfma_f32_16x16x32_bf16 v[104:107], v[136:139], v[188:191], 0
	v_mfma_f32_16x16x32_bf16 v[96:99], v[128:131], v[196:199], 0
	v_mfma_f32_16x16x32_bf16 v[88:91], v[136:139], v[196:199], 0
	v_mfma_f32_16x16x32_bf16 v[80:83], v[128:131], v[210:213], 0
	v_mfma_f32_16x16x32_bf16 v[72:75], v[136:139], v[210:213], 0
	v_mfma_f32_16x16x32_bf16 v[124:127], v[132:135], v[184:187], v[124:127]
	v_mfma_f32_16x16x32_bf16 v[120:123], v[140:143], v[184:187], v[120:123]
	v_mfma_f32_16x16x32_bf16 v[112:115], v[132:135], v[192:195], v[112:115]
	v_mfma_f32_16x16x32_bf16 v[104:107], v[140:143], v[192:195], v[104:107]
	v_mfma_f32_16x16x32_bf16 v[96:99], v[132:135], v[206:209], v[96:99]
	v_mfma_f32_16x16x32_bf16 v[88:91], v[140:143], v[206:209], v[88:91]
	v_mfma_f32_16x16x32_bf16 v[80:83], v[132:135], v[214:217], v[80:83]
	v_mfma_f32_16x16x32_bf16 v[72:75], v[140:143], v[214:217], v[72:75]
	s_setprio 0
	s_setprio 1
	v_mfma_f32_16x16x32_bf16 v[116:119], v[156:159], v[180:183], 0
	v_mfma_f32_16x16x32_bf16 v[108:111], v[168:171], v[180:183], 0
	v_mfma_f32_16x16x32_bf16 v[100:103], v[156:159], v[188:191], 0
	v_mfma_f32_16x16x32_bf16 v[92:95], v[168:171], v[188:191], 0
	v_mfma_f32_16x16x32_bf16 v[84:87], v[156:159], v[196:199], 0
	v_mfma_f32_16x16x32_bf16 v[76:79], v[168:171], v[196:199], 0
	v_mfma_f32_16x16x32_bf16 v[68:71], v[156:159], v[210:213], 0
	v_mfma_f32_16x16x32_bf16 v[64:67], v[168:171], v[210:213], 0
	v_mfma_f32_16x16x32_bf16 v[116:119], v[164:167], v[184:187], v[116:119]
	v_mfma_f32_16x16x32_bf16 v[108:111], v[176:179], v[184:187], v[108:111]
	v_mfma_f32_16x16x32_bf16 v[100:103], v[164:167], v[192:195], v[100:103]
	v_mfma_f32_16x16x32_bf16 v[92:95], v[176:179], v[192:195], v[92:95]
	v_mfma_f32_16x16x32_bf16 v[84:87], v[164:167], v[206:209], v[84:87]
	v_mfma_f32_16x16x32_bf16 v[76:79], v[176:179], v[206:209], v[76:79]
	v_mfma_f32_16x16x32_bf16 v[68:71], v[164:167], v[214:217], v[68:71]
	v_mfma_f32_16x16x32_bf16 v[64:67], v[176:179], v[214:217], v[64:67]
	s_barrier
	s_setprio 0
	s_add_i32 s18, s18, s46
	v_lshl_add_u64 v[200:201], s[50:51], 0, v[148:149]
	s_mov_b32 m0, s18
	ds_read_b128 v[180:183], v175 offset:16384
	ds_read_b128 v[184:187], v175 offset:17408
	ds_read_b128 v[188:191], v175 offset:18432
	ds_read_b128 v[192:195], v175 offset:19456
	ds_read_b128 v[196:199], v175 offset:20480
	ds_read_b128 v[206:209], v175 offset:21504
	ds_read_b128 v[210:213], v175 offset:22528
	ds_read_b128 v[214:217], v175 offset:23552
	global_load_lds_dwordx4 v[200:201], off
	s_add_i32 m0, s18, 0x2000
	s_add_u32 s18, s50, 0xb0000
	v_lshl_add_u64 v[218:219], s[50:51], 0, v[144:145]
	s_addc_u32 s19, s51, 0
	s_add_i32 s20, s20, s46
	global_load_lds_dwordx4 v[218:219], off
	v_lshl_add_u64 v[220:221], s[18:19], 0, v[148:149]
	s_mov_b32 m0, s20
	v_lshl_add_u64 v[222:223], s[58:59], 0, v[146:147]
	global_load_lds_dwordx4 v[220:221], off
	v_lshl_add_u64 v[220:221], s[18:19], 0, v[144:145]
	s_add_i32 m0, s20, 0x2000
	s_nop 0
	global_load_lds_dwordx4 v[220:221], off
	v_lshl_add_u64 v[220:221], s[58:59], 0, v[150:151]
	s_mov_b32 m0, s4
	s_nop 0
	global_load_lds_dwordx4 v[220:221], off
	s_mov_b32 m0, s5
	s_nop 0
	global_load_lds_dwordx4 v[222:223], off
	s_waitcnt vmcnt(8)
	s_waitcnt lgkmcnt(0)
	s_setprio 1
	s_barrier
	v_mfma_f32_16x16x32_bf16 v[60:63], v[128:131], v[180:183], 0
	v_mfma_f32_16x16x32_bf16 v[56:59], v[136:139], v[180:183], 0
	v_mfma_f32_16x16x32_bf16 v[48:51], v[128:131], v[188:191], 0
	v_mfma_f32_16x16x32_bf16 v[40:43], v[136:139], v[188:191], 0
	v_mfma_f32_16x16x32_bf16 v[32:35], v[128:131], v[196:199], 0
	v_mfma_f32_16x16x32_bf16 v[24:27], v[136:139], v[196:199], 0
	v_mfma_f32_16x16x32_bf16 v[16:19], v[128:131], v[210:213], 0
	v_mfma_f32_16x16x32_bf16 v[8:11], v[136:139], v[210:213], 0
	v_mfma_f32_16x16x32_bf16 v[60:63], v[132:135], v[184:187], v[60:63]
	v_mfma_f32_16x16x32_bf16 v[56:59], v[140:143], v[184:187], v[56:59]
	v_mfma_f32_16x16x32_bf16 v[48:51], v[132:135], v[192:195], v[48:51]
	v_mfma_f32_16x16x32_bf16 v[40:43], v[140:143], v[192:195], v[40:43]
	v_mfma_f32_16x16x32_bf16 v[32:35], v[132:135], v[206:209], v[32:35]
	v_mfma_f32_16x16x32_bf16 v[24:27], v[140:143], v[206:209], v[24:27]
	v_mfma_f32_16x16x32_bf16 v[16:19], v[132:135], v[214:217], v[16:19]
	v_mfma_f32_16x16x32_bf16 v[8:11], v[140:143], v[214:217], v[8:11]
	s_setprio 0
	s_setprio 1
	v_mfma_f32_16x16x32_bf16 v[52:55], v[156:159], v[180:183], 0
	v_mfma_f32_16x16x32_bf16 v[44:47], v[168:171], v[180:183], 0
	v_mfma_f32_16x16x32_bf16 v[36:39], v[156:159], v[188:191], 0
	v_mfma_f32_16x16x32_bf16 v[28:31], v[168:171], v[188:191], 0
	v_mfma_f32_16x16x32_bf16 v[20:23], v[156:159], v[196:199], 0
	v_mfma_f32_16x16x32_bf16 v[12:15], v[168:171], v[196:199], 0
	v_mfma_f32_16x16x32_bf16 v[4:7], v[156:159], v[210:213], 0
	v_mfma_f32_16x16x32_bf16 v[0:3], v[168:171], v[210:213], 0
	v_mfma_f32_16x16x32_bf16 v[52:55], v[164:167], v[184:187], v[52:55]
	v_mfma_f32_16x16x32_bf16 v[44:47], v[176:179], v[184:187], v[44:47]
	v_mfma_f32_16x16x32_bf16 v[36:39], v[164:167], v[192:195], v[36:39]
	v_mfma_f32_16x16x32_bf16 v[28:31], v[176:179], v[192:195], v[28:31]
	v_mfma_f32_16x16x32_bf16 v[20:23], v[164:167], v[206:209], v[20:23]
	v_mfma_f32_16x16x32_bf16 v[12:15], v[176:179], v[206:209], v[12:15]
	v_mfma_f32_16x16x32_bf16 v[4:7], v[164:167], v[214:217], v[4:7]
	v_mfma_f32_16x16x32_bf16 v[0:3], v[176:179], v[214:217], v[0:3]
	s_barrier
	s_setprio 0
	s_add_i32 s20, 0, 0x18000
	s_add_i32 s21, 0, 0x1c000
	v_add_u32_e32 v140, s20, v174
	v_add_u32_e32 v162, s21, v174
	ds_read_b128 v[128:131], v140
	ds_read_b128 v[132:135], v140 offset:1024
	ds_read_b128 v[136:139], v140 offset:2048
	ds_read_b128 v[140:143], v140 offset:3072
	ds_read_b128 v[156:159], v162
	ds_read_b128 v[164:167], v162 offset:1024
	ds_read_b128 v[168:171], v162 offset:2048
	ds_read_b128 v[176:179], v162 offset:3072
	s_add_u32 s18, s58, 0xb0000
	s_addc_u32 s19, s59, 0
	s_mov_b32 m0, s6
	v_lshl_add_u64 v[224:225], s[18:19], 0, v[150:151]
	ds_read_b128 v[180:183], v175 offset:32768
	ds_read_b128 v[184:187], v175 offset:33792
	ds_read_b128 v[188:191], v175 offset:34816
	ds_read_b128 v[192:195], v175 offset:35840
	ds_read_b128 v[196:199], v175 offset:36864
	ds_read_b128 v[206:209], v175 offset:37888
	ds_read_b128 v[210:213], v175 offset:38912
	ds_read_b128 v[214:217], v175 offset:39936
	global_load_lds_dwordx4 v[224:225], off
	v_lshl_add_u64 v[224:225], s[18:19], 0, v[146:147]
	s_mov_b32 m0, s7
	s_nop 0
	global_load_lds_dwordx4 v[224:225], off
	s_waitcnt vmcnt(8)
	s_waitcnt lgkmcnt(0)
	s_setprio 1
	s_barrier
	v_mfma_f32_16x16x32_bf16 v[124:127], v[128:131], v[180:183], v[124:127]
	v_mfma_f32_16x16x32_bf16 v[120:123], v[136:139], v[180:183], v[120:123]
	v_mfma_f32_16x16x32_bf16 v[112:115], v[128:131], v[188:191], v[112:115]
	v_mfma_f32_16x16x32_bf16 v[104:107], v[136:139], v[188:191], v[104:107]
	v_mfma_f32_16x16x32_bf16 v[96:99], v[128:131], v[196:199], v[96:99]
	v_mfma_f32_16x16x32_bf16 v[88:91], v[136:139], v[196:199], v[88:91]
	v_mfma_f32_16x16x32_bf16 v[80:83], v[128:131], v[210:213], v[80:83]
	v_mfma_f32_16x16x32_bf16 v[72:75], v[136:139], v[210:213], v[72:75]
	v_mfma_f32_16x16x32_bf16 v[124:127], v[132:135], v[184:187], v[124:127]
	v_mfma_f32_16x16x32_bf16 v[120:123], v[140:143], v[184:187], v[120:123]
	v_mfma_f32_16x16x32_bf16 v[112:115], v[132:135], v[192:195], v[112:115]
	v_mfma_f32_16x16x32_bf16 v[104:107], v[140:143], v[192:195], v[104:107]
	v_mfma_f32_16x16x32_bf16 v[96:99], v[132:135], v[206:209], v[96:99]
	v_mfma_f32_16x16x32_bf16 v[88:91], v[140:143], v[206:209], v[88:91]
	v_mfma_f32_16x16x32_bf16 v[80:83], v[132:135], v[214:217], v[80:83]
	v_mfma_f32_16x16x32_bf16 v[72:75], v[140:143], v[214:217], v[72:75]
	s_setprio 0
	s_setprio 1
	v_mfma_f32_16x16x32_bf16 v[116:119], v[156:159], v[180:183], v[116:119]
	v_mfma_f32_16x16x32_bf16 v[108:111], v[168:171], v[180:183], v[108:111]
	v_mfma_f32_16x16x32_bf16 v[100:103], v[156:159], v[188:191], v[100:103]
	v_mfma_f32_16x16x32_bf16 v[92:95], v[168:171], v[188:191], v[92:95]
	v_mfma_f32_16x16x32_bf16 v[84:87], v[156:159], v[196:199], v[84:87]
	v_mfma_f32_16x16x32_bf16 v[76:79], v[168:171], v[196:199], v[76:79]
	v_mfma_f32_16x16x32_bf16 v[68:71], v[156:159], v[210:213], v[68:71]
	v_mfma_f32_16x16x32_bf16 v[64:67], v[168:171], v[210:213], v[64:67]
	v_mfma_f32_16x16x32_bf16 v[116:119], v[164:167], v[184:187], v[116:119]
	v_mfma_f32_16x16x32_bf16 v[108:111], v[176:179], v[184:187], v[108:111]
	v_mfma_f32_16x16x32_bf16 v[100:103], v[164:167], v[192:195], v[100:103]
	v_mfma_f32_16x16x32_bf16 v[92:95], v[176:179], v[192:195], v[92:95]
	v_mfma_f32_16x16x32_bf16 v[84:87], v[164:167], v[206:209], v[84:87]
	v_mfma_f32_16x16x32_bf16 v[76:79], v[176:179], v[206:209], v[76:79]
	v_mfma_f32_16x16x32_bf16 v[68:71], v[164:167], v[214:217], v[68:71]
	v_mfma_f32_16x16x32_bf16 v[64:67], v[176:179], v[214:217], v[64:67]
	s_barrier
	s_setprio 0
	s_add_i32 s18, s20, s46
	v_lshl_add_u64 v[200:201], v[200:201], 0, s[76:77]
	s_mov_b32 m0, s18
	ds_read_b128 v[180:183], v175 offset:49152
	ds_read_b128 v[184:187], v175 offset:50176
	ds_read_b128 v[188:191], v175 offset:51200
	ds_read_b128 v[192:195], v175 offset:52224
	ds_read_b128 v[196:199], v175 offset:53248
	ds_read_b128 v[206:209], v175 offset:54272
	ds_read_b128 v[210:213], v175 offset:55296
	ds_read_b128 v[214:217], v175 offset:56320
	global_load_lds_dwordx4 v[200:201], off
	s_add_i32 m0, s18, 0x2000
	s_add_u32 s18, s50, 0xb0080
	v_lshl_add_u64 v[200:201], v[218:219], 0, s[76:77]
	s_addc_u32 s19, s51, 0
	s_add_i32 s20, s21, s46
	global_load_lds_dwordx4 v[200:201], off
	v_lshl_add_u64 v[200:201], s[18:19], 0, v[148:149]
	s_mov_b32 m0, s20
	s_nop 0
	global_load_lds_dwordx4 v[200:201], off
	v_lshl_add_u64 v[200:201], s[18:19], 0, v[144:145]
	s_add_i32 m0, s20, 0x2000
	s_nop 0
	global_load_lds_dwordx4 v[200:201], off
	v_lshl_add_u64 v[200:201], v[220:221], 0, s[76:77]
	s_mov_b32 m0, s11
	s_nop 0
	global_load_lds_dwordx4 v[200:201], off
	v_lshl_add_u64 v[200:201], v[222:223], 0, s[76:77]
	s_mov_b32 m0, s12
	s_nop 0
	global_load_lds_dwordx4 v[200:201], off
	s_add_i32 s61, s61, 2
	s_add_u32 s54, s54, 0x100
	s_addc_u32 s60, s60, 0
	s_mov_b64 s[42:43], s[48:49]
	s_cmp_gt_u32 s61, 41
	s_cbranch_scc1 .Lrs_1210_a
	s_add_u32 s48, s42, 0x100
	s_addc_u32 s49, s43, 0
	s_add_i32 s18, 0, 0x10000
	s_cmp_eq_u32 s61, 40
	s_cselect_b32 s59, s39, s49
	s_cselect_b32 s58, s38, s48
	s_cselect_b32 s51, s41, s60
	s_cselect_b32 s50, s40, s54
	s_add_i32 s20, 0, 0x14000
.Lrs_1210_a:
	s_waitcnt vmcnt(8)
	s_waitcnt lgkmcnt(0)
	s_setprio 1
	s_barrier
	v_mfma_f32_16x16x32_bf16 v[60:63], v[128:131], v[180:183], v[60:63]
	v_mfma_f32_16x16x32_bf16 v[56:59], v[136:139], v[180:183], v[56:59]
	v_mfma_f32_16x16x32_bf16 v[48:51], v[128:131], v[188:191], v[48:51]
	v_mfma_f32_16x16x32_bf16 v[40:43], v[136:139], v[188:191], v[40:43]
	v_mfma_f32_16x16x32_bf16 v[32:35], v[128:131], v[196:199], v[32:35]
	v_mfma_f32_16x16x32_bf16 v[24:27], v[136:139], v[196:199], v[24:27]
	v_mfma_f32_16x16x32_bf16 v[16:19], v[128:131], v[210:213], v[16:19]
	v_mfma_f32_16x16x32_bf16 v[8:11], v[136:139], v[210:213], v[8:11]
	v_mfma_f32_16x16x32_bf16 v[60:63], v[132:135], v[184:187], v[60:63]
	v_mfma_f32_16x16x32_bf16 v[56:59], v[140:143], v[184:187], v[56:59]
	v_mfma_f32_16x16x32_bf16 v[48:51], v[132:135], v[192:195], v[48:51]
	v_mfma_f32_16x16x32_bf16 v[40:43], v[140:143], v[192:195], v[40:43]
	v_mfma_f32_16x16x32_bf16 v[32:35], v[132:135], v[206:209], v[32:35]
	v_mfma_f32_16x16x32_bf16 v[24:27], v[140:143], v[206:209], v[24:27]
	v_mfma_f32_16x16x32_bf16 v[16:19], v[132:135], v[214:217], v[16:19]
	v_mfma_f32_16x16x32_bf16 v[8:11], v[140:143], v[214:217], v[8:11]
	s_setprio 0
	s_setprio 1
	v_mfma_f32_16x16x32_bf16 v[52:55], v[156:159], v[180:183], v[52:55]
	v_mfma_f32_16x16x32_bf16 v[44:47], v[168:171], v[180:183], v[44:47]
	v_mfma_f32_16x16x32_bf16 v[36:39], v[156:159], v[188:191], v[36:39]
	v_mfma_f32_16x16x32_bf16 v[28:31], v[168:171], v[188:191], v[28:31]
	v_mfma_f32_16x16x32_bf16 v[20:23], v[156:159], v[196:199], v[20:23]
	v_mfma_f32_16x16x32_bf16 v[12:15], v[168:171], v[196:199], v[12:15]
	v_mfma_f32_16x16x32_bf16 v[4:7], v[156:159], v[210:213], v[4:7]
	v_mfma_f32_16x16x32_bf16 v[0:3], v[168:171], v[210:213], v[0:3]
	v_mfma_f32_16x16x32_bf16 v[52:55], v[164:167], v[184:187], v[52:55]
	v_mfma_f32_16x16x32_bf16 v[44:47], v[176:179], v[184:187], v[44:47]
	v_mfma_f32_16x16x32_bf16 v[36:39], v[164:167], v[192:195], v[36:39]
	v_mfma_f32_16x16x32_bf16 v[28:31], v[176:179], v[192:195], v[28:31]
	v_mfma_f32_16x16x32_bf16 v[20:23], v[164:167], v[206:209], v[20:23]
	v_mfma_f32_16x16x32_bf16 v[12:15], v[176:179], v[206:209], v[12:15]
	v_mfma_f32_16x16x32_bf16 v[4:7], v[164:167], v[214:217], v[4:7]
	v_mfma_f32_16x16x32_bf16 v[0:3], v[176:179], v[214:217], v[0:3]
	s_barrier
	s_setprio 0
	s_cmp_gt_u32 s61, 41
	s_cbranch_scc0 .Lrot_1210
	s_branch .Lpeel_x_1210
.LBB0_1210:
.Lrot_1210:
	v_add_u32_e32 v140, s18, v174
	v_add_u32_e32 v162, s20, v174
	ds_read_b128 v[128:131], v140
	ds_read_b128 v[132:135], v140 offset:1024
	ds_read_b128 v[136:139], v140 offset:2048
	ds_read_b128 v[140:143], v140 offset:3072
	ds_read_b128 v[156:159], v162
	ds_read_b128 v[164:167], v162 offset:1024
	ds_read_b128 v[168:171], v162 offset:2048
	ds_read_b128 v[176:179], v162 offset:3072
	v_lshl_add_u64 v[200:201], s[42:43], 0, v[152:153]
	s_add_i32 m0, s4, 0xc000
	ds_read_b128 v[180:183], v175
	ds_read_b128 v[184:187], v175 offset:1024
	ds_read_b128 v[188:191], v175 offset:2048
	ds_read_b128 v[192:195], v175 offset:3072
	ds_read_b128 v[196:199], v175 offset:4096
	ds_read_b128 v[206:209], v175 offset:5120
	ds_read_b128 v[210:213], v175 offset:6144
	ds_read_b128 v[214:217], v175 offset:7168
	global_load_lds_dwordx4 v[200:201], off
	v_lshl_add_u64 v[200:201], s[42:43], 0, v[154:155]
	s_add_i32 m0, s4, 0xe000
	s_nop 0
	global_load_lds_dwordx4 v[200:201], off
	s_waitcnt vmcnt(8)
	s_waitcnt lgkmcnt(0)
	s_setprio 1
	s_barrier
	v_mfma_f32_16x16x32_bf16 v[124:127], v[128:131], v[180:183], v[124:127]
	v_mfma_f32_16x16x32_bf16 v[120:123], v[136:139], v[180:183], v[120:123]
	v_mfma_f32_16x16x32_bf16 v[112:115], v[128:131], v[188:191], v[112:115]
	v_mfma_f32_16x16x32_bf16 v[104:107], v[136:139], v[188:191], v[104:107]
	v_mfma_f32_16x16x32_bf16 v[96:99], v[128:131], v[196:199], v[96:99]
	v_mfma_f32_16x16x32_bf16 v[88:91], v[136:139], v[196:199], v[88:91]
	v_mfma_f32_16x16x32_bf16 v[80:83], v[128:131], v[210:213], v[80:83]
	v_mfma_f32_16x16x32_bf16 v[72:75], v[136:139], v[210:213], v[72:75]
	v_mfma_f32_16x16x32_bf16 v[124:127], v[132:135], v[184:187], v[124:127]
	v_mfma_f32_16x16x32_bf16 v[120:123], v[140:143], v[184:187], v[120:123]
	v_mfma_f32_16x16x32_bf16 v[112:115], v[132:135], v[192:195], v[112:115]
	v_mfma_f32_16x16x32_bf16 v[104:107], v[140:143], v[192:195], v[104:107]
	v_mfma_f32_16x16x32_bf16 v[96:99], v[132:135], v[206:209], v[96:99]
	v_mfma_f32_16x16x32_bf16 v[88:91], v[140:143], v[206:209], v[88:91]
	v_mfma_f32_16x16x32_bf16 v[80:83], v[132:135], v[214:217], v[80:83]
	v_mfma_f32_16x16x32_bf16 v[72:75], v[140:143], v[214:217], v[72:75]
	s_setprio 0
	s_setprio 1
	v_mfma_f32_16x16x32_bf16 v[116:119], v[156:159], v[180:183], v[116:119]
	v_mfma_f32_16x16x32_bf16 v[108:111], v[168:171], v[180:183], v[108:111]
	v_mfma_f32_16x16x32_bf16 v[100:103], v[156:159], v[188:191], v[100:103]
	v_mfma_f32_16x16x32_bf16 v[92:95], v[168:171], v[188:191], v[92:95]
	v_mfma_f32_16x16x32_bf16 v[84:87], v[156:159], v[196:199], v[84:87]
	v_mfma_f32_16x16x32_bf16 v[76:79], v[168:171], v[196:199], v[76:79]
	v_mfma_f32_16x16x32_bf16 v[68:71], v[156:159], v[210:213], v[68:71]
	v_mfma_f32_16x16x32_bf16 v[64:67], v[168:171], v[210:213], v[64:67]
	v_mfma_f32_16x16x32_bf16 v[116:119], v[164:167], v[184:187], v[116:119]
	v_mfma_f32_16x16x32_bf16 v[108:111], v[176:179], v[184:187], v[108:111]
	v_mfma_f32_16x16x32_bf16 v[100:103], v[164:167], v[192:195], v[100:103]
	v_mfma_f32_16x16x32_bf16 v[92:95], v[176:179], v[192:195], v[92:95]
	v_mfma_f32_16x16x32_bf16 v[84:87], v[164:167], v[206:209], v[84:87]
	v_mfma_f32_16x16x32_bf16 v[76:79], v[176:179], v[206:209], v[76:79]
	v_mfma_f32_16x16x32_bf16 v[68:71], v[164:167], v[214:217], v[68:71]
	v_mfma_f32_16x16x32_bf16 v[64:67], v[176:179], v[214:217], v[64:67]
	s_barrier
	s_setprio 0
	s_add_i32 s18, s18, s46
	v_lshl_add_u64 v[200:201], s[50:51], 0, v[148:149]
	s_mov_b32 m0, s18
	ds_read_b128 v[180:183], v175 offset:16384
	ds_read_b128 v[184:187], v175 offset:17408
	ds_read_b128 v[188:191], v175 offset:18432
	ds_read_b128 v[192:195], v175 offset:19456
	ds_read_b128 v[196:199], v175 offset:20480
	ds_read_b128 v[206:209], v175 offset:21504
	ds_read_b128 v[210:213], v175 offset:22528
	ds_read_b128 v[214:217], v175 offset:23552
	global_load_lds_dwordx4 v[200:201], off
	s_add_i32 m0, s18, 0x2000
	s_add_u32 s18, s50, 0xb0000
	v_lshl_add_u64 v[218:219], s[50:51], 0, v[144:145]
	s_addc_u32 s19, s51, 0
	s_add_i32 s20, s20, s46
	global_load_lds_dwordx4 v[218:219], off
	v_lshl_add_u64 v[220:221], s[18:19], 0, v[148:149]
	s_mov_b32 m0, s20
	v_lshl_add_u64 v[222:223], s[58:59], 0, v[146:147]
	global_load_lds_dwordx4 v[220:221], off
	v_lshl_add_u64 v[220:221], s[18:19], 0, v[144:145]
	s_add_i32 m0, s20, 0x2000
	s_nop 0
	global_load_lds_dwordx4 v[220:221], off
	v_lshl_add_u64 v[220:221], s[58:59], 0, v[150:151]
	s_mov_b32 m0, s4
	s_nop 0
	global_load_lds_dwordx4 v[220:221], off
	s_mov_b32 m0, s5
	s_nop 0
	global_load_lds_dwordx4 v[222:223], off
	s_waitcnt vmcnt(8)
	s_waitcnt lgkmcnt(0)
	s_setprio 1
	s_barrier
	v_mfma_f32_16x16x32_bf16 v[60:63], v[128:131], v[180:183], v[60:63]
	v_mfma_f32_16x16x32_bf16 v[56:59], v[136:139], v[180:183], v[56:59]
	v_mfma_f32_16x16x32_bf16 v[48:51], v[128:131], v[188:191], v[48:51]
	v_mfma_f32_16x16x32_bf16 v[40:43], v[136:139], v[188:191], v[40:43]
	v_mfma_f32_16x16x32_bf16 v[32:35], v[128:131], v[196:199], v[32:35]
	v_mfma_f32_16x16x32_bf16 v[24:27], v[136:139], v[196:199], v[24:27]
	v_mfma_f32_16x16x32_bf16 v[16:19], v[128:131], v[210:213], v[16:19]
	v_mfma_f32_16x16x32_bf16 v[8:11], v[136:139], v[210:213], v[8:11]
	v_mfma_f32_16x16x32_bf16 v[60:63], v[132:135], v[184:187], v[60:63]
	v_mfma_f32_16x16x32_bf16 v[56:59], v[140:143], v[184:187], v[56:59]
	v_mfma_f32_16x16x32_bf16 v[48:51], v[132:135], v[192:195], v[48:51]
	v_mfma_f32_16x16x32_bf16 v[40:43], v[140:143], v[192:195], v[40:43]
	v_mfma_f32_16x16x32_bf16 v[32:35], v[132:135], v[206:209], v[32:35]
	v_mfma_f32_16x16x32_bf16 v[24:27], v[140:143], v[206:209], v[24:27]
	v_mfma_f32_16x16x32_bf16 v[16:19], v[132:135], v[214:217], v[16:19]
	v_mfma_f32_16x16x32_bf16 v[8:11], v[140:143], v[214:217], v[8:11]
	s_setprio 0
	s_setprio 1
	v_mfma_f32_16x16x32_bf16 v[52:55], v[156:159], v[180:183], v[52:55]
	v_mfma_f32_16x16x32_bf16 v[44:47], v[168:171], v[180:183], v[44:47]
	v_mfma_f32_16x16x32_bf16 v[36:39], v[156:159], v[188:191], v[36:39]
	v_mfma_f32_16x16x32_bf16 v[28:31], v[168:171], v[188:191], v[28:31]
	v_mfma_f32_16x16x32_bf16 v[20:23], v[156:159], v[196:199], v[20:23]
	v_mfma_f32_16x16x32_bf16 v[12:15], v[168:171], v[196:199], v[12:15]
	v_mfma_f32_16x16x32_bf16 v[4:7], v[156:159], v[210:213], v[4:7]
	v_mfma_f32_16x16x32_bf16 v[0:3], v[168:171], v[210:213], v[0:3]
	v_mfma_f32_16x16x32_bf16 v[52:55], v[164:167], v[184:187], v[52:55]
	v_mfma_f32_16x16x32_bf16 v[44:47], v[176:179], v[184:187], v[44:47]
	v_mfma_f32_16x16x32_bf16 v[36:39], v[164:167], v[192:195], v[36:39]
	v_mfma_f32_16x16x32_bf16 v[28:31], v[176:179], v[192:195], v[28:31]
	v_mfma_f32_16x16x32_bf16 v[20:23], v[164:167], v[206:209], v[20:23]
	v_mfma_f32_16x16x32_bf16 v[12:15], v[176:179], v[206:209], v[12:15]
	v_mfma_f32_16x16x32_bf16 v[4:7], v[164:167], v[214:217], v[4:7]
	v_mfma_f32_16x16x32_bf16 v[0:3], v[176:179], v[214:217], v[0:3]
	s_barrier
	s_setprio 0
	s_add_i32 s20, 0, 0x18000
	s_add_i32 s21, 0, 0x1c000
	v_add_u32_e32 v140, s20, v174
	v_add_u32_e32 v162, s21, v174
	ds_read_b128 v[128:131], v140
	ds_read_b128 v[132:135], v140 offset:1024
	ds_read_b128 v[136:139], v140 offset:2048
	ds_read_b128 v[140:143], v140 offset:3072
	ds_read_b128 v[156:159], v162
	ds_read_b128 v[164:167], v162 offset:1024
	ds_read_b128 v[168:171], v162 offset:2048
	ds_read_b128 v[176:179], v162 offset:3072
	s_add_u32 s18, s58, 0xb0000
	s_addc_u32 s19, s59, 0
	s_mov_b32 m0, s6
	v_lshl_add_u64 v[224:225], s[18:19], 0, v[150:151]
	ds_read_b128 v[180:183], v175 offset:32768
	ds_read_b128 v[184:187], v175 offset:33792
	ds_read_b128 v[188:191], v175 offset:34816
	ds_read_b128 v[192:195], v175 offset:35840
	ds_read_b128 v[196:199], v175 offset:36864
	ds_read_b128 v[206:209], v175 offset:37888
	ds_read_b128 v[210:213], v175 offset:38912
	ds_read_b128 v[214:217], v175 offset:39936
	global_load_lds_dwordx4 v[224:225], off
	v_lshl_add_u64 v[224:225], s[18:19], 0, v[146:147]
	s_mov_b32 m0, s7
	s_nop 0
	global_load_lds_dwordx4 v[224:225], off
	s_waitcnt vmcnt(8)
	s_waitcnt lgkmcnt(0)
	s_setprio 1
	s_barrier
	v_mfma_f32_16x16x32_bf16 v[124:127], v[128:131], v[180:183], v[124:127]
	v_mfma_f32_16x16x32_bf16 v[120:123], v[136:139], v[180:183], v[120:123]
	v_mfma_f32_16x16x32_bf16 v[112:115], v[128:131], v[188:191], v[112:115]
	v_mfma_f32_16x16x32_bf16 v[104:107], v[136:139], v[188:191], v[104:107]
	v_mfma_f32_16x16x32_bf16 v[96:99], v[128:131], v[196:199], v[96:99]
	v_mfma_f32_16x16x32_bf16 v[88:91], v[136:139], v[196:199], v[88:91]
	v_mfma_f32_16x16x32_bf16 v[80:83], v[128:131], v[210:213], v[80:83]
	v_mfma_f32_16x16x32_bf16 v[72:75], v[136:139], v[210:213], v[72:75]
	v_mfma_f32_16x16x32_bf16 v[124:127], v[132:135], v[184:187], v[124:127]
	v_mfma_f32_16x16x32_bf16 v[120:123], v[140:143], v[184:187], v[120:123]
	v_mfma_f32_16x16x32_bf16 v[112:115], v[132:135], v[192:195], v[112:115]
	v_mfma_f32_16x16x32_bf16 v[104:107], v[140:143], v[192:195], v[104:107]
	v_mfma_f32_16x16x32_bf16 v[96:99], v[132:135], v[206:209], v[96:99]
	v_mfma_f32_16x16x32_bf16 v[88:91], v[140:143], v[206:209], v[88:91]
	v_mfma_f32_16x16x32_bf16 v[80:83], v[132:135], v[214:217], v[80:83]
	v_mfma_f32_16x16x32_bf16 v[72:75], v[140:143], v[214:217], v[72:75]
	s_setprio 0
	s_setprio 1
	v_mfma_f32_16x16x32_bf16 v[116:119], v[156:159], v[180:183], v[116:119]
	v_mfma_f32_16x16x32_bf16 v[108:111], v[168:171], v[180:183], v[108:111]
	v_mfma_f32_16x16x32_bf16 v[100:103], v[156:159], v[188:191], v[100:103]
	v_mfma_f32_16x16x32_bf16 v[92:95], v[168:171], v[188:191], v[92:95]
	v_mfma_f32_16x16x32_bf16 v[84:87], v[156:159], v[196:199], v[84:87]
	v_mfma_f32_16x16x32_bf16 v[76:79], v[168:171], v[196:199], v[76:79]
	v_mfma_f32_16x16x32_bf16 v[68:71], v[156:159], v[210:213], v[68:71]
	v_mfma_f32_16x16x32_bf16 v[64:67], v[168:171], v[210:213], v[64:67]
	v_mfma_f32_16x16x32_bf16 v[116:119], v[164:167], v[184:187], v[116:119]
	v_mfma_f32_16x16x32_bf16 v[108:111], v[176:179], v[184:187], v[108:111]
	v_mfma_f32_16x16x32_bf16 v[100:103], v[164:167], v[192:195], v[100:103]
	v_mfma_f32_16x16x32_bf16 v[92:95], v[176:179], v[192:195], v[92:95]
	v_mfma_f32_16x16x32_bf16 v[84:87], v[164:167], v[206:209], v[84:87]
	v_mfma_f32_16x16x32_bf16 v[76:79], v[176:179], v[206:209], v[76:79]
	v_mfma_f32_16x16x32_bf16 v[68:71], v[164:167], v[214:217], v[68:71]
	v_mfma_f32_16x16x32_bf16 v[64:67], v[176:179], v[214:217], v[64:67]
	s_barrier
	s_setprio 0
	s_add_i32 s18, s20, s46
	v_lshl_add_u64 v[200:201], v[200:201], 0, s[76:77]
	s_mov_b32 m0, s18
	ds_read_b128 v[180:183], v175 offset:49152
	ds_read_b128 v[184:187], v175 offset:50176
	ds_read_b128 v[188:191], v175 offset:51200
	ds_read_b128 v[192:195], v175 offset:52224
	ds_read_b128 v[196:199], v175 offset:53248
	ds_read_b128 v[206:209], v175 offset:54272
	ds_read_b128 v[210:213], v175 offset:55296
	ds_read_b128 v[214:217], v175 offset:56320
	global_load_lds_dwordx4 v[200:201], off
	s_add_i32 m0, s18, 0x2000
	s_add_u32 s18, s50, 0xb0080
	v_lshl_add_u64 v[200:201], v[218:219], 0, s[76:77]
	s_addc_u32 s19, s51, 0
	s_add_i32 s20, s21, s46
	global_load_lds_dwordx4 v[200:201], off
	v_lshl_add_u64 v[200:201], s[18:19], 0, v[148:149]
	s_mov_b32 m0, s20
	s_nop 0
	global_load_lds_dwordx4 v[200:201], off
	v_lshl_add_u64 v[200:201], s[18:19], 0, v[144:145]
	s_add_i32 m0, s20, 0x2000
	s_nop 0
	global_load_lds_dwordx4 v[200:201], off
	v_lshl_add_u64 v[200:201], v[220:221], 0, s[76:77]
	s_mov_b32 m0, s11
	s_nop 0
	global_load_lds_dwordx4 v[200:201], off
	v_lshl_add_u64 v[200:201], v[222:223], 0, s[76:77]
	s_mov_b32 m0, s12
	s_nop 0
	global_load_lds_dwordx4 v[200:201], off
	s_add_i32 s61, s61, 2
	s_add_u32 s54, s54, 0x100
	s_addc_u32 s60, s60, 0
	s_mov_b64 s[42:43], s[48:49]
	s_cmp_gt_u32 s61, 41
	s_cbranch_scc1 .Lrs_1210_b
	s_add_u32 s48, s42, 0x100
	s_addc_u32 s49, s43, 0
	s_add_i32 s18, 0, 0x10000
	s_cmp_eq_u32 s61, 40
	s_cselect_b32 s59, s39, s49
	s_cselect_b32 s58, s38, s48
	s_cselect_b32 s51, s41, s60
	s_cselect_b32 s50, s40, s54
	s_add_i32 s20, 0, 0x14000
.Lrs_1210_b:
	s_waitcnt vmcnt(8)
	s_waitcnt lgkmcnt(0)
	s_setprio 1
	s_barrier
	v_mfma_f32_16x16x32_bf16 v[60:63], v[128:131], v[180:183], v[60:63]
	v_mfma_f32_16x16x32_bf16 v[56:59], v[136:139], v[180:183], v[56:59]
	v_mfma_f32_16x16x32_bf16 v[48:51], v[128:131], v[188:191], v[48:51]
	v_mfma_f32_16x16x32_bf16 v[40:43], v[136:139], v[188:191], v[40:43]
	v_mfma_f32_16x16x32_bf16 v[32:35], v[128:131], v[196:199], v[32:35]
	v_mfma_f32_16x16x32_bf16 v[24:27], v[136:139], v[196:199], v[24:27]
	v_mfma_f32_16x16x32_bf16 v[16:19], v[128:131], v[210:213], v[16:19]
	v_mfma_f32_16x16x32_bf16 v[8:11], v[136:139], v[210:213], v[8:11]
	v_mfma_f32_16x16x32_bf16 v[60:63], v[132:135], v[184:187], v[60:63]
	v_mfma_f32_16x16x32_bf16 v[56:59], v[140:143], v[184:187], v[56:59]
	v_mfma_f32_16x16x32_bf16 v[48:51], v[132:135], v[192:195], v[48:51]
	v_mfma_f32_16x16x32_bf16 v[40:43], v[140:143], v[192:195], v[40:43]
	v_mfma_f32_16x16x32_bf16 v[32:35], v[132:135], v[206:209], v[32:35]
	v_mfma_f32_16x16x32_bf16 v[24:27], v[140:143], v[206:209], v[24:27]
	v_mfma_f32_16x16x32_bf16 v[16:19], v[132:135], v[214:217], v[16:19]
	v_mfma_f32_16x16x32_bf16 v[8:11], v[140:143], v[214:217], v[8:11]
	s_setprio 0
	s_setprio 1
	v_mfma_f32_16x16x32_bf16 v[52:55], v[156:159], v[180:183], v[52:55]
	v_mfma_f32_16x16x32_bf16 v[44:47], v[168:171], v[180:183], v[44:47]
	v_mfma_f32_16x16x32_bf16 v[36:39], v[156:159], v[188:191], v[36:39]
	v_mfma_f32_16x16x32_bf16 v[28:31], v[168:171], v[188:191], v[28:31]
	v_mfma_f32_16x16x32_bf16 v[20:23], v[156:159], v[196:199], v[20:23]
	v_mfma_f32_16x16x32_bf16 v[12:15], v[168:171], v[196:199], v[12:15]
	v_mfma_f32_16x16x32_bf16 v[4:7], v[156:159], v[210:213], v[4:7]
	v_mfma_f32_16x16x32_bf16 v[0:3], v[168:171], v[210:213], v[0:3]
	v_mfma_f32_16x16x32_bf16 v[52:55], v[164:167], v[184:187], v[52:55]
	v_mfma_f32_16x16x32_bf16 v[44:47], v[176:179], v[184:187], v[44:47]
	v_mfma_f32_16x16x32_bf16 v[36:39], v[164:167], v[192:195], v[36:39]
	v_mfma_f32_16x16x32_bf16 v[28:31], v[176:179], v[192:195], v[28:31]
	v_mfma_f32_16x16x32_bf16 v[20:23], v[164:167], v[206:209], v[20:23]
	v_mfma_f32_16x16x32_bf16 v[12:15], v[176:179], v[206:209], v[12:15]
	v_mfma_f32_16x16x32_bf16 v[4:7], v[164:167], v[214:217], v[4:7]
	v_mfma_f32_16x16x32_bf16 v[0:3], v[176:179], v[214:217], v[0:3]
	s_barrier
	s_setprio 0
	s_cmp_gt_u32 s61, 41
	s_cbranch_scc0 .Lrot_1210
